# v80 + diff loops: next-step K addresses, next-tile V read base and DMA offsets computed in the QK MFMA chain gaps (now that the MFMA run holds the highest priority)
# speedup vs baseline: 1.0077x; 1.0077x over previous
; #define SBAR() __builtin_amdgcn_sched_barrier(0)
; #define ATT_DMA_K(t) do { const bf16_t* kg_ = Kh + (size_t)(t) * 64 * LDK; LAS unsigned char* sb_ = lds + ((t) & 3) * KBUF; \
;     _Pragma("unroll") for (int i_ = 0; i_ < NKP; ++i_) __builtin_amdgcn_global_load_lds((const unsigned*)(kg_ + kgo[i_]), (LAS unsigned*)(sb_ + (wid + 8 * i_) * 1024), 16, 0, 0); } while (0)
; #define ATT_DMA_V(t, vs) do { const bf16_t* vg_ = Vh + (size_t)(t) * 64 * LDV; LAS unsigned char* sb_ = lds + V_OFF + (vs) * SHM_V; \
;     _Pragma("unroll") for (int i_ = 0; i_ < 2; ++i_) __builtin_amdgcn_global_load_lds((const unsigned*)(vg_ + vgo[i_]), (LAS unsigned*)(sb_ + (2 * wid + i_) * 1024), 16, 0, 0); } while (0)
; #define ATT_SEG(t) do { if constexpr (MODE != 0) { if (((t) == tL && tL > 0) || (t) == tR) { const float f_ = (t) == tR ? fR : fL; l_reg *= f_; \
;     _Pragma("unroll") for (int d = 0; d < 4; ++d) _Pragma("unroll") for (int r = 0; r < 16; ++r) o[d][r] *= f_; } } } while (0)
; #define ATT_TOP(N) do { asm volatile("s_waitcnt vmcnt(%0)" :: "n"(N) : "memory"); __builtin_amdgcn_s_barrier(); asm volatile("" ::: "memory"); } while (0)
; DI void expsum(f32x16& p, float& l_reg, bf16x8& pa0, bf16x8& pa1) {
; #pragma unroll
;     for (int r = 0; r < 16; ++r) p[r] = __builtin_amdgcn_exp2f(p[r]);
;     float ps = 0.f;
; #pragma unroll
;     for (int r = 0; r < 16; ++r) ps += p[r];
;     l_reg += ps; asm volatile("" : "+v"(l_reg));
;     ...
;     ATT_PK4(p, 0, pa0); ATT_PK4(p, 8, pa1);
;     ...
; }
; template <int DQK, int MODE, int LDQ, int LDK, int LDV> ...
;     ...
;     f32x16 pA, pB; bf16x8 pa0, pa1;
;     int v0 = 0, v1 = 1, v2 = 2;
;     ATT_TOP(NKP + 2);
;     { bf16x8 kf[NDA]; k_reads<DQK, 0, NDA>(kf, lds, 0, r32, hi); ATT_LGKM0(); qk_mma<0, NDA>(pA, kf, qr);
;       if constexpr (ND0 > NDA) { bf16x8 kg[ND0 - NDA]; k_reads<DQK, NDA, ND0>(kg, lds, 0, r32, hi); ATT_LGKM0(); qk_mma<NDA, ND0>(pA, kg, qr); }
;       ATT_BIAS(pA, 0, 0); }
;     if (wid >= 4) __builtin_amdgcn_s_setprio(1);
;     for (int j = 0; j < NT; ++j) {
;         if (j + 2 < NT) ATT_TOP(NKP + 2); else ATT_TOP(0);
;         if (j + 3 < NT) ATT_DMA_K(j + 3);
;         if (j + 2 < NT) ATT_DMA_V(j + 2, v2);
;         ATT_SEG(j); SBAR();
;         ATT_STEP(pA, pB, 0, v0, true, 1, j);
;         ATT_STEP(pB, pA, 1, v0, (j + 1 < NT), 0, j + 1);
;         { const int t_ = v0; v0 = v1; v1 = v2; v2 = t_; }
;     }
.Lhw_d0_b_n1922:
	ds_read_b128 v[122:125], v196 offset:4096
	ds_read_b128 v[132:135], v197 offset:4096
	s_lshl_b32 s2, s1, 14
	ds_read_b128 v[136:139], v198 offset:4096
	ds_read_b128 v[140:143], v199 offset:4096
	ds_read_b64_tr_b16 v[144:145], v121 offset:0
	ds_read_b64_tr_b16 v[146:147], v121 offset:0x800
	ds_read_b64_tr_b16 v[148:149], v121 offset:0x1000
	ds_read_b64_tr_b16 v[150:151], v121 offset:0x1800
	ds_read_b64_tr_b16 v[152:153], v121 offset:0x200
	ds_read_b64_tr_b16 v[154:155], v121 offset:0xa00
	ds_read_b64_tr_b16 v[156:157], v121 offset:0x1200
	ds_read_b64_tr_b16 v[158:159], v121 offset:0x1a00
	ds_read_b64_tr_b16 v[162:163], v121 offset:0x400
	ds_read_b64_tr_b16 v[164:165], v121 offset:0xc00
	ds_read_b64_tr_b16 v[166:167], v121 offset:0x1400
	ds_read_b64_tr_b16 v[168:169], v121 offset:0x1c00
	ds_read_b64_tr_b16 v[170:171], v121 offset:0x600
	ds_read_b64_tr_b16 v[172:173], v121 offset:0xe00
	ds_read_b64_tr_b16 v[174:175], v121 offset:0x1600
	ds_read_b64_tr_b16 v[176:177], v121 offset:0x1e00
	s_setprio 1
	v_exp_f32_e32 v64, v64
	v_exp_f32_e32 v65, v65
	v_exp_f32_e32 v66, v66
	v_exp_f32_e32 v67, v67
	v_exp_f32_e32 v68, v68
	v_exp_f32_e32 v69, v69
	v_add_f32_e32 v126, v65, v64
	v_exp_f32_e32 v70, v70
	v_add_f32_e32 v126, v66, v126
	v_exp_f32_e32 v71, v71
	v_add_f32_e32 v126, v67, v126
	v_exp_f32_e32 v72, v72
	v_add_f32_e32 v126, v68, v126
	v_exp_f32_e32 v73, v73
	v_add_f32_e32 v126, v69, v126
	v_exp_f32_e32 v74, v74
	v_add_f32_e32 v126, v70, v126
	v_exp_f32_e32 v75, v75
	v_add_f32_e32 v126, v71, v126
	v_exp_f32_e32 v76, v76
	v_add_f32_e32 v126, v72, v126
	v_exp_f32_e32 v77, v77
	v_add_f32_e32 v126, v73, v126
	v_exp_f32_e32 v78, v78
	v_add_f32_e32 v126, v74, v126
	v_exp_f32_e32 v79, v79
	v_add_f32_e32 v126, v75, v126
	v_add_f32_e32 v126, v76, v126
	v_add_f32_e32 v126, v77, v126
	v_add_f32_e32 v126, v78, v126
	v_add_f32_e32 v126, v79, v126
	v_add_f32_e32 v120, v126, v120
	v_cvt_pk_bf16_f32 v64, v64, v65
	v_cvt_pk_bf16_f32 v65, v66, v67
	v_cvt_pk_bf16_f32 v66, v68, v69
	v_cvt_pk_bf16_f32 v67, v70, v71
	v_cvt_pk_bf16_f32 v68, v72, v73
	v_cvt_pk_bf16_f32 v69, v74, v75
	v_cvt_pk_bf16_f32 v70, v76, v77
	v_cvt_pk_bf16_f32 v71, v78, v79
	s_waitcnt lgkmcnt(0)
	s_setprio 2
	v_mfma_f32_32x32x16_bf16 v[0:15], v[64:67], v[144:147], v[0:15]
	s_add_i32 s74, s22, 0xffffc000
	s_and_b32 s74, s74, 0x6000
	s_sub_i32 s3, s0, s98
	s_cmp_lt_u32 s3, s100
	v_mfma_f32_32x32x16_bf16 v[48:63], v[64:67], v[152:155], v[48:63]
	v_mfma_f32_32x32x16_bf16 v[32:47], v[64:67], v[162:165], v[32:47]
	v_mfma_f32_32x32x16_bf16 v[16:31], v[64:67], v[170:173], v[16:31]
	v_mfma_f32_32x32x16_bf16 v[0:15], v[68:71], v[148:151], v[0:15]
	v_mfma_f32_32x32x16_bf16 v[48:63], v[68:71], v[156:159], v[48:63]
	v_mfma_f32_32x32x16_bf16 v[32:47], v[68:71], v[166:169], v[32:47]
	v_mfma_f32_32x32x16_bf16 v[16:31], v[68:71], v[174:177], v[16:31]
	v_add_u32_e32 v196, s74, v107
	v_mfma_f32_32x32x16_bf16 v[64:79], v[122:125], v[92:95], 0
	v_add_u32_e32 v197, s74, v108
	v_mfma_f32_32x32x16_bf16 v[64:79], v[132:135], v[88:91], v[64:79]
	v_add_u32_e32 v198, s74, v109
	v_mfma_f32_32x32x16_bf16 v[64:79], v[136:139], v[84:87], v[64:79]
	v_add_u32_e32 v199, s74, v110
	v_mfma_f32_32x32x16_bf16 v[64:79], v[140:143], v[80:83], v[64:79]
	s_setprio 0
	s_cbranch_scc1 .Lhw_d0_b_dtd0bias1
.Lhw_d0_b_n1924:
	ds_read_b128 v[124:127], v196
	ds_read_b128 v[132:135], v197
	ds_read_b128 v[136:139], v198
	ds_read_b128 v[140:143], v199
	ds_read_b64_tr_b16 v[144:145], v121 offset:0x2000
	ds_read_b64_tr_b16 v[146:147], v121 offset:0x2800
	ds_read_b64_tr_b16 v[148:149], v121 offset:0x3000
	ds_read_b64_tr_b16 v[150:151], v121 offset:0x3800
	ds_read_b64_tr_b16 v[152:153], v121 offset:0x2200
	ds_read_b64_tr_b16 v[154:155], v121 offset:0x2a00
	ds_read_b64_tr_b16 v[156:157], v121 offset:0x3200
	ds_read_b64_tr_b16 v[158:159], v121 offset:0x3a00
	ds_read_b64_tr_b16 v[162:163], v121 offset:0x2400
	ds_read_b64_tr_b16 v[164:165], v121 offset:0x2c00
	ds_read_b64_tr_b16 v[166:167], v121 offset:0x3400
	ds_read_b64_tr_b16 v[168:169], v121 offset:0x3c00
	ds_read_b64_tr_b16 v[170:171], v121 offset:0x2600
	ds_read_b64_tr_b16 v[172:173], v121 offset:0x2e00
	ds_read_b64_tr_b16 v[174:175], v121 offset:0x3600
	ds_read_b64_tr_b16 v[176:177], v121 offset:0x3e00
	s_setprio 1
	v_exp_f32_e32 v64, v64
	v_exp_f32_e32 v65, v65
	v_exp_f32_e32 v66, v66
	v_exp_f32_e32 v67, v67
	v_exp_f32_e32 v68, v68
	v_exp_f32_e32 v69, v69
	v_add_f32_e32 v121, v65, v64
	v_exp_f32_e32 v70, v70
	v_add_f32_e32 v121, v66, v121
	v_exp_f32_e32 v71, v71
	v_add_f32_e32 v121, v67, v121
	v_exp_f32_e32 v72, v72
	v_add_f32_e32 v121, v68, v121
	v_exp_f32_e32 v73, v73
	v_add_f32_e32 v121, v69, v121
	v_exp_f32_e32 v74, v74
	v_add_f32_e32 v121, v70, v121
	v_exp_f32_e32 v75, v75
	v_add_f32_e32 v121, v71, v121
	v_exp_f32_e32 v76, v76
	v_add_f32_e32 v121, v72, v121
	v_exp_f32_e32 v77, v77
	v_add_f32_e32 v121, v73, v121
	v_exp_f32_e32 v78, v78
	v_add_f32_e32 v121, v74, v121
	v_exp_f32_e32 v79, v79
	v_add_f32_e32 v121, v75, v121
	v_add_f32_e32 v121, v76, v121
	v_add_f32_e32 v121, v77, v121
	v_add_f32_e32 v121, v78, v121
	v_add_f32_e32 v121, v79, v121
	v_add_f32_e32 v120, v120, v121
	v_cvt_pk_bf16_f32 v64, v64, v65
	v_cvt_pk_bf16_f32 v65, v66, v67
	v_cvt_pk_bf16_f32 v66, v68, v69
	v_cvt_pk_bf16_f32 v67, v70, v71
	v_cvt_pk_bf16_f32 v68, v72, v73
	v_cvt_pk_bf16_f32 v69, v74, v75
	v_cvt_pk_bf16_f32 v70, v76, v77
	v_cvt_pk_bf16_f32 v71, v78, v79
	s_waitcnt lgkmcnt(0)
	s_setprio 2
	s_waitcnt vmcnt(3)
	s_barrier
	v_mfma_f32_32x32x16_bf16 v[0:15], v[64:67], v[144:147], v[0:15]
	s_sub_i32 s74, s0, s55
	s_cmp_lt_u32 s74, s100
	v_mfma_f32_32x32x16_bf16 v[48:63], v[64:67], v[152:155], v[48:63]
	v_mfma_f32_32x32x16_bf16 v[32:47], v[64:67], v[162:165], v[32:47]
	v_mfma_f32_32x32x16_bf16 v[16:31], v[64:67], v[170:173], v[16:31]
	v_mfma_f32_32x32x16_bf16 v[0:15], v[68:71], v[148:151], v[0:15]
	v_mfma_f32_32x32x16_bf16 v[48:63], v[68:71], v[156:159], v[48:63]
	v_mfma_f32_32x32x16_bf16 v[32:47], v[68:71], v[166:169], v[32:47]
	v_mfma_f32_32x32x16_bf16 v[16:31], v[68:71], v[174:177], v[16:31]
	v_lshl_add_u32 v121, s64, 14, v106
	v_mfma_f32_32x32x16_bf16 v[64:79], v[124:127], v[92:95], 0
	v_add_u32_e32 v100, s8, v100
	v_mfma_f32_32x32x16_bf16 v[64:79], v[132:135], v[88:91], v[64:79]
	v_add_u32_e32 v102, s8, v102
	v_mfma_f32_32x32x16_bf16 v[64:79], v[136:139], v[84:87], v[64:79]
	v_add_u32_e32 v104, s8, v104
	v_mfma_f32_32x32x16_bf16 v[64:79], v[140:143], v[80:83], v[64:79]
	s_cbranch_scc1 .Lhw_d0_b_dtd0bias2

; #define SBAR() __builtin_amdgcn_sched_barrier(0)
; #define ATT_DMA_K(t) do { const bf16_t* kg_ = Kh + (size_t)(t) * 64 * LDK; LAS unsigned char* sb_ = lds + ((t) & 3) * KBUF; \
;     _Pragma("unroll") for (int i_ = 0; i_ < NKP; ++i_) __builtin_amdgcn_global_load_lds((const unsigned*)(kg_ + kgo[i_]), (LAS unsigned*)(sb_ + (wid + 8 * i_) * 1024), 16, 0, 0); } while (0)
; #define ATT_DMA_V(t, vs) do { const bf16_t* vg_ = Vh + (size_t)(t) * 64 * LDV; LAS unsigned char* sb_ = lds + V_OFF + (vs) * SHM_V; \
;     _Pragma("unroll") for (int i_ = 0; i_ < 2; ++i_) __builtin_amdgcn_global_load_lds((const unsigned*)(vg_ + vgo[i_]), (LAS unsigned*)(sb_ + (2 * wid + i_) * 1024), 16, 0, 0); } while (0)
; #define ATT_SEG(t) do { if constexpr (MODE != 0) { if (((t) == tL && tL > 0) || (t) == tR) { const float f_ = (t) == tR ? fR : fL; l_reg *= f_; \
;     _Pragma("unroll") for (int d = 0; d < 4; ++d) _Pragma("unroll") for (int r = 0; r < 16; ++r) o[d][r] *= f_; } } } while (0)
; #define ATT_TOP(N) do { asm volatile("s_waitcnt vmcnt(%0)" :: "n"(N) : "memory"); __builtin_amdgcn_s_barrier(); asm volatile("" ::: "memory"); } while (0)
; DI void expsum(f32x16& p, float& l_reg, bf16x8& pa0, bf16x8& pa1) {
; #pragma unroll
;     for (int r = 0; r < 16; ++r) p[r] = __builtin_amdgcn_exp2f(p[r]);
;     float ps = 0.f;
; #pragma unroll
;     for (int r = 0; r < 16; ++r) ps += p[r];
;     l_reg += ps; asm volatile("" : "+v"(l_reg));
;     ...
;     ATT_PK4(p, 0, pa0); ATT_PK4(p, 8, pa1);
;     ...
; }
; template <int DQK, int MODE, int LDQ, int LDK, int LDV> ...
;     ...
;     f32x16 pA, pB; bf16x8 pa0, pa1;
;     int v0 = 0, v1 = 1, v2 = 2;
;     ATT_TOP(NKP + 2);
;     { bf16x8 kf[NDA]; k_reads<DQK, 0, NDA>(kf, lds, 0, r32, hi); ATT_LGKM0(); qk_mma<0, NDA>(pA, kf, qr);
;       if constexpr (ND0 > NDA) { bf16x8 kg[ND0 - NDA]; k_reads<DQK, NDA, ND0>(kg, lds, 0, r32, hi); ATT_LGKM0(); qk_mma<NDA, ND0>(pA, kg, qr); }
;       ATT_BIAS(pA, 0, 0); }
;     if (wid >= 4) __builtin_amdgcn_s_setprio(1);
;     for (int j = 0; j < NT; ++j) {
;         if (j + 2 < NT) ATT_TOP(NKP + 2); else ATT_TOP(0);
;         if (j + 3 < NT) ATT_DMA_K(j + 3);
;         if (j + 2 < NT) ATT_DMA_V(j + 2, v2);
;         ATT_SEG(j); SBAR();
;         ATT_STEP(pA, pB, 0, v0, true, 1, j);
;         ATT_STEP(pB, pA, 1, v0, (j + 1 < NT), 0, j + 1);
;         { const int t_ = v0; v0 = v1; v1 = v2; v2 = t_; }
;     }
.LBB0_1924:
	ds_read_b128 v[124:127], v196
	ds_read_b128 v[132:135], v197
	ds_read_b128 v[136:139], v198
	ds_read_b128 v[140:143], v199
	ds_read_b64_tr_b16 v[144:145], v121 offset:0x2000
	ds_read_b64_tr_b16 v[146:147], v121 offset:0x2800
	ds_read_b64_tr_b16 v[148:149], v121 offset:0x3000
	ds_read_b64_tr_b16 v[150:151], v121 offset:0x3800
	ds_read_b64_tr_b16 v[152:153], v121 offset:0x2200
	ds_read_b64_tr_b16 v[154:155], v121 offset:0x2a00
	ds_read_b64_tr_b16 v[156:157], v121 offset:0x3200
	ds_read_b64_tr_b16 v[158:159], v121 offset:0x3a00
	ds_read_b64_tr_b16 v[162:163], v121 offset:0x2400
	ds_read_b64_tr_b16 v[164:165], v121 offset:0x2c00
	ds_read_b64_tr_b16 v[166:167], v121 offset:0x3400
	ds_read_b64_tr_b16 v[168:169], v121 offset:0x3c00
	ds_read_b64_tr_b16 v[170:171], v121 offset:0x2600
	ds_read_b64_tr_b16 v[172:173], v121 offset:0x2e00
	ds_read_b64_tr_b16 v[174:175], v121 offset:0x3600
	ds_read_b64_tr_b16 v[176:177], v121 offset:0x3e00
	s_setprio 1
	v_exp_f32_e32 v64, v64
	v_exp_f32_e32 v65, v65
	v_exp_f32_e32 v66, v66
	v_exp_f32_e32 v67, v67
	v_exp_f32_e32 v68, v68
	v_exp_f32_e32 v69, v69
	v_add_f32_e32 v121, v65, v64
	v_exp_f32_e32 v70, v70
	v_add_f32_e32 v121, v66, v121
	v_exp_f32_e32 v71, v71
	v_add_f32_e32 v121, v67, v121
	v_exp_f32_e32 v72, v72
	v_add_f32_e32 v121, v68, v121
	v_exp_f32_e32 v73, v73
	v_add_f32_e32 v121, v69, v121
	v_exp_f32_e32 v74, v74
	v_add_f32_e32 v121, v70, v121
	v_exp_f32_e32 v75, v75
	v_add_f32_e32 v121, v71, v121
	v_exp_f32_e32 v76, v76
	v_add_f32_e32 v121, v72, v121
	v_exp_f32_e32 v77, v77
	v_add_f32_e32 v121, v73, v121
	v_exp_f32_e32 v78, v78
	v_add_f32_e32 v121, v74, v121
	v_exp_f32_e32 v79, v79
	v_add_f32_e32 v121, v75, v121
	v_add_f32_e32 v121, v76, v121
	v_add_f32_e32 v121, v77, v121
	v_add_f32_e32 v121, v78, v121
	v_add_f32_e32 v121, v79, v121
	v_add_f32_e32 v120, v120, v121
	v_cvt_pk_bf16_f32 v64, v64, v65
	v_cvt_pk_bf16_f32 v65, v66, v67
	v_cvt_pk_bf16_f32 v66, v68, v69
	v_cvt_pk_bf16_f32 v67, v70, v71
	v_cvt_pk_bf16_f32 v68, v72, v73
	v_cvt_pk_bf16_f32 v69, v74, v75
	v_cvt_pk_bf16_f32 v70, v76, v77
	v_cvt_pk_bf16_f32 v71, v78, v79
	s_waitcnt lgkmcnt(0)
	s_setprio 2
	v_mfma_f32_32x32x16_bf16 v[0:15], v[64:67], v[144:147], v[0:15]
	s_sub_i32 s74, s0, s55
	s_cmp_lt_u32 s74, s100
	v_mfma_f32_32x32x16_bf16 v[48:63], v[64:67], v[152:155], v[48:63]
	v_mfma_f32_32x32x16_bf16 v[32:47], v[64:67], v[162:165], v[32:47]
	v_mfma_f32_32x32x16_bf16 v[16:31], v[64:67], v[170:173], v[16:31]
	v_mfma_f32_32x32x16_bf16 v[0:15], v[68:71], v[148:151], v[0:15]
	v_mfma_f32_32x32x16_bf16 v[48:63], v[68:71], v[156:159], v[48:63]
	v_mfma_f32_32x32x16_bf16 v[32:47], v[68:71], v[166:169], v[32:47]
	v_mfma_f32_32x32x16_bf16 v[16:31], v[68:71], v[174:177], v[16:31]
	v_lshl_add_u32 v121, s64, 14, v106
	v_mfma_f32_32x32x16_bf16 v[64:79], v[124:127], v[92:95], 0
	v_add_u32_e32 v100, s8, v100
	v_mfma_f32_32x32x16_bf16 v[64:79], v[132:135], v[88:91], v[64:79]
	v_add_u32_e32 v102, s8, v102
	v_mfma_f32_32x32x16_bf16 v[64:79], v[136:139], v[84:87], v[64:79]
	v_add_u32_e32 v104, s8, v104
	v_mfma_f32_32x32x16_bf16 v[64:79], v[140:143], v[80:83], v[64:79]
	s_cbranch_scc1 .Ldt_d0_bias2

; #define SBAR() __builtin_amdgcn_sched_barrier(0)
; #define ATT_DMA_K(t) do { const bf16_t* kg_ = Kh + (size_t)(t) * 64 * LDK; LAS unsigned char* sb_ = lds + ((t) & 3) * KBUF; \
;     _Pragma("unroll") for (int i_ = 0; i_ < NKP; ++i_) __builtin_amdgcn_global_load_lds((const unsigned*)(kg_ + kgo[i_]), (LAS unsigned*)(sb_ + (wid + 8 * i_) * 1024), 16, 0, 0); } while (0)
; #define ATT_DMA_V(t, vs) do { const bf16_t* vg_ = Vh + (size_t)(t) * 64 * LDV; LAS unsigned char* sb_ = lds + V_OFF + (vs) * SHM_V; \
;     _Pragma("unroll") for (int i_ = 0; i_ < 2; ++i_) __builtin_amdgcn_global_load_lds((const unsigned*)(vg_ + vgo[i_]), (LAS unsigned*)(sb_ + (2 * wid + i_) * 1024), 16, 0, 0); } while (0)
; #define ATT_SEG(t) do { if constexpr (MODE != 0) { if (((t) == tL && tL > 0) || (t) == tR) { const float f_ = (t) == tR ? fR : fL; l_reg *= f_; \
;     _Pragma("unroll") for (int d = 0; d < 4; ++d) _Pragma("unroll") for (int r = 0; r < 16; ++r) o[d][r] *= f_; } } } while (0)
; #define ATT_TOP(N) do { asm volatile("s_waitcnt vmcnt(%0)" :: "n"(N) : "memory"); __builtin_amdgcn_s_barrier(); asm volatile("" ::: "memory"); } while (0)
; DI void expsum(f32x16& p, float& l_reg, bf16x8& pa0, bf16x8& pa1) {
; #pragma unroll
;     for (int r = 0; r < 16; ++r) p[r] = __builtin_amdgcn_exp2f(p[r]);
;     float ps = 0.f;
; #pragma unroll
;     for (int r = 0; r < 16; ++r) ps += p[r];
;     l_reg += ps; asm volatile("" : "+v"(l_reg));
;     ...
;     ATT_PK4(p, 0, pa0); ATT_PK4(p, 8, pa1);
;     ...
; }
; template <int DQK, int MODE, int LDQ, int LDK, int LDV> ...
;     ...
;     f32x16 pA, pB; bf16x8 pa0, pa1;
;     int v0 = 0, v1 = 1, v2 = 2;
;     ATT_TOP(NKP + 2);
;     { bf16x8 kf[NDA]; k_reads<DQK, 0, NDA>(kf, lds, 0, r32, hi); ATT_LGKM0(); qk_mma<0, NDA>(pA, kf, qr);
;       if constexpr (ND0 > NDA) { bf16x8 kg[ND0 - NDA]; k_reads<DQK, NDA, ND0>(kg, lds, 0, r32, hi); ATT_LGKM0(); qk_mma<NDA, ND0>(pA, kg, qr); }
;       ATT_BIAS(pA, 0, 0); }
;     if (wid >= 4) __builtin_amdgcn_s_setprio(1);
;     for (int j = 0; j < NT; ++j) {
;         if (j + 2 < NT) ATT_TOP(NKP + 2); else ATT_TOP(0);
;         if (j + 3 < NT) ATT_DMA_K(j + 3);
;         if (j + 2 < NT) ATT_DMA_V(j + 2, v2);
;         ATT_SEG(j); SBAR();
;         ATT_STEP(pA, pB, 0, v0, true, 1, j);
;         ATT_STEP(pB, pA, 1, v0, (j + 1 < NT), 0, j + 1);
;         { const int t_ = v0; v0 = v1; v1 = v2; v2 = t_; }
;     }
.Lhw_d1_b_n1953:
	ds_read_b128 v[122:125], v196 offset:4096
	ds_read_b128 v[132:135], v197 offset:4096
	s_lshl_b32 s2, s23, 14
	ds_read_b128 v[136:139], v198 offset:4096
	ds_read_b128 v[140:143], v199 offset:4096
	ds_read_b64_tr_b16 v[144:145], v121 offset:0
	ds_read_b64_tr_b16 v[146:147], v121 offset:0x800
	ds_read_b64_tr_b16 v[148:149], v121 offset:0x1000
	ds_read_b64_tr_b16 v[150:151], v121 offset:0x1800
	ds_read_b64_tr_b16 v[152:153], v121 offset:0x200
	ds_read_b64_tr_b16 v[154:155], v121 offset:0xa00
	ds_read_b64_tr_b16 v[156:157], v121 offset:0x1200
	ds_read_b64_tr_b16 v[158:159], v121 offset:0x1a00
	ds_read_b64_tr_b16 v[162:163], v121 offset:0x400
	ds_read_b64_tr_b16 v[164:165], v121 offset:0xc00
	ds_read_b64_tr_b16 v[166:167], v121 offset:0x1400
	ds_read_b64_tr_b16 v[168:169], v121 offset:0x1c00
	ds_read_b64_tr_b16 v[170:171], v121 offset:0x600
	ds_read_b64_tr_b16 v[172:173], v121 offset:0xe00
	ds_read_b64_tr_b16 v[174:175], v121 offset:0x1600
	ds_read_b64_tr_b16 v[176:177], v121 offset:0x1e00
	s_setprio 1
	v_exp_f32_e32 v64, v64
	v_exp_f32_e32 v65, v65
	v_exp_f32_e32 v66, v66
	v_exp_f32_e32 v67, v67
	v_exp_f32_e32 v68, v68
	v_exp_f32_e32 v69, v69
	v_add_f32_e32 v126, v65, v64
	v_exp_f32_e32 v70, v70
	v_add_f32_e32 v126, v66, v126
	v_exp_f32_e32 v71, v71
	v_add_f32_e32 v126, v67, v126
	v_exp_f32_e32 v72, v72
	v_add_f32_e32 v126, v68, v126
	v_exp_f32_e32 v73, v73
	v_add_f32_e32 v126, v69, v126
	v_exp_f32_e32 v74, v74
	v_add_f32_e32 v126, v70, v126
	v_exp_f32_e32 v75, v75
	v_add_f32_e32 v126, v71, v126
	v_exp_f32_e32 v76, v76
	v_add_f32_e32 v126, v72, v126
	v_exp_f32_e32 v77, v77
	v_add_f32_e32 v126, v73, v126
	v_exp_f32_e32 v78, v78
	v_add_f32_e32 v126, v74, v126
	v_exp_f32_e32 v79, v79
	v_add_f32_e32 v126, v75, v126
	v_add_f32_e32 v126, v76, v126
	v_add_f32_e32 v126, v77, v126
	v_add_f32_e32 v126, v78, v126
	v_add_f32_e32 v126, v79, v126
	v_add_f32_e32 v120, v126, v120
	v_cvt_pk_bf16_f32 v64, v64, v65
	v_cvt_pk_bf16_f32 v65, v66, v67
	v_cvt_pk_bf16_f32 v66, v68, v69
	v_cvt_pk_bf16_f32 v67, v70, v71
	v_cvt_pk_bf16_f32 v68, v72, v73
	v_cvt_pk_bf16_f32 v69, v74, v75
	v_cvt_pk_bf16_f32 v70, v76, v77
	v_cvt_pk_bf16_f32 v71, v78, v79
	s_waitcnt lgkmcnt(0)
	s_setprio 2
	v_mfma_f32_32x32x16_bf16 v[0:15], v[64:67], v[144:147], v[0:15]
	s_add_i32 s74, s22, 0xffffc000
	s_and_b32 s74, s74, 0x6000
	s_sub_i32 s3, s0, s98
	s_cmp_lt_u32 s3, s100
	v_mfma_f32_32x32x16_bf16 v[48:63], v[64:67], v[152:155], v[48:63]
	v_mfma_f32_32x32x16_bf16 v[16:31], v[64:67], v[162:165], v[16:31]
	v_mfma_f32_32x32x16_bf16 v[32:47], v[64:67], v[170:173], v[32:47]
	v_mfma_f32_32x32x16_bf16 v[0:15], v[68:71], v[148:151], v[0:15]
	v_mfma_f32_32x32x16_bf16 v[48:63], v[68:71], v[156:159], v[48:63]
	v_mfma_f32_32x32x16_bf16 v[16:31], v[68:71], v[166:169], v[16:31]
	v_mfma_f32_32x32x16_bf16 v[32:47], v[68:71], v[174:177], v[32:47]
	v_add_u32_e32 v196, s74, v107
	v_mfma_f32_32x32x16_bf16 v[64:79], v[122:125], v[92:95], 0
	v_add_u32_e32 v197, s74, v108
	v_mfma_f32_32x32x16_bf16 v[64:79], v[132:135], v[88:91], v[64:79]
	v_add_u32_e32 v198, s74, v109
	v_mfma_f32_32x32x16_bf16 v[64:79], v[136:139], v[84:87], v[64:79]
	v_add_u32_e32 v199, s74, v110
	v_mfma_f32_32x32x16_bf16 v[64:79], v[140:143], v[80:83], v[64:79]
	s_setprio 0
	s_cbranch_scc1 .Lhw_d1_b_dtd1bias1
.Lhw_d1_b_n1955:
	ds_read_b128 v[124:127], v196
	ds_read_b128 v[132:135], v197
	ds_read_b128 v[136:139], v198
	ds_read_b128 v[140:143], v199
	ds_read_b64_tr_b16 v[144:145], v121 offset:0x2000
	ds_read_b64_tr_b16 v[146:147], v121 offset:0x2800
	ds_read_b64_tr_b16 v[148:149], v121 offset:0x3000
	ds_read_b64_tr_b16 v[150:151], v121 offset:0x3800
	ds_read_b64_tr_b16 v[152:153], v121 offset:0x2200
	ds_read_b64_tr_b16 v[154:155], v121 offset:0x2a00
	ds_read_b64_tr_b16 v[156:157], v121 offset:0x3200
	ds_read_b64_tr_b16 v[158:159], v121 offset:0x3a00
	ds_read_b64_tr_b16 v[162:163], v121 offset:0x2400
	ds_read_b64_tr_b16 v[164:165], v121 offset:0x2c00
	ds_read_b64_tr_b16 v[166:167], v121 offset:0x3400
	ds_read_b64_tr_b16 v[168:169], v121 offset:0x3c00
	ds_read_b64_tr_b16 v[170:171], v121 offset:0x2600
	ds_read_b64_tr_b16 v[172:173], v121 offset:0x2e00
	ds_read_b64_tr_b16 v[174:175], v121 offset:0x3600
	ds_read_b64_tr_b16 v[176:177], v121 offset:0x3e00
	s_setprio 1
	v_exp_f32_e32 v64, v64
	v_exp_f32_e32 v65, v65
	v_exp_f32_e32 v66, v66
	v_exp_f32_e32 v67, v67
	v_exp_f32_e32 v68, v68
	v_exp_f32_e32 v69, v69
	v_add_f32_e32 v121, v65, v64
	v_exp_f32_e32 v70, v70
	v_add_f32_e32 v121, v66, v121
	v_exp_f32_e32 v71, v71
	v_add_f32_e32 v121, v67, v121
	v_exp_f32_e32 v72, v72
	v_add_f32_e32 v121, v68, v121
	v_exp_f32_e32 v73, v73
	v_add_f32_e32 v121, v69, v121
	v_exp_f32_e32 v74, v74
	v_add_f32_e32 v121, v70, v121
	v_exp_f32_e32 v75, v75
	v_add_f32_e32 v121, v71, v121
	v_exp_f32_e32 v76, v76
	v_add_f32_e32 v121, v72, v121
	v_exp_f32_e32 v77, v77
	v_add_f32_e32 v121, v73, v121
	v_exp_f32_e32 v78, v78
	v_add_f32_e32 v121, v74, v121
	v_exp_f32_e32 v79, v79
	v_add_f32_e32 v121, v75, v121
	v_add_f32_e32 v121, v76, v121
	v_add_f32_e32 v121, v77, v121
	v_add_f32_e32 v121, v78, v121
	v_add_f32_e32 v121, v79, v121
	v_add_f32_e32 v120, v120, v121
	v_cvt_pk_bf16_f32 v64, v64, v65
	v_cvt_pk_bf16_f32 v65, v66, v67
	v_cvt_pk_bf16_f32 v66, v68, v69
	v_cvt_pk_bf16_f32 v67, v70, v71
	v_cvt_pk_bf16_f32 v68, v72, v73
	v_cvt_pk_bf16_f32 v69, v74, v75
	v_cvt_pk_bf16_f32 v70, v76, v77
	v_cvt_pk_bf16_f32 v71, v78, v79
	s_waitcnt lgkmcnt(0)
	s_setprio 2
	s_waitcnt vmcnt(3)
	s_barrier
	v_mfma_f32_32x32x16_bf16 v[0:15], v[64:67], v[144:147], v[0:15]
	s_sub_i32 s74, s0, s47
	s_cmp_lt_u32 s74, s100
	v_mfma_f32_32x32x16_bf16 v[48:63], v[64:67], v[152:155], v[48:63]
	v_mfma_f32_32x32x16_bf16 v[16:31], v[64:67], v[162:165], v[16:31]
	v_mfma_f32_32x32x16_bf16 v[32:47], v[64:67], v[170:173], v[32:47]
	v_mfma_f32_32x32x16_bf16 v[0:15], v[68:71], v[148:151], v[0:15]
	v_mfma_f32_32x32x16_bf16 v[48:63], v[68:71], v[156:159], v[48:63]
	v_mfma_f32_32x32x16_bf16 v[16:31], v[68:71], v[166:169], v[16:31]
	v_mfma_f32_32x32x16_bf16 v[32:47], v[68:71], v[174:177], v[32:47]
	v_lshl_add_u32 v121, s49, 14, v106
	v_mfma_f32_32x32x16_bf16 v[64:79], v[124:127], v[92:95], 0
	v_add_u32_e32 v100, s8, v100
	v_mfma_f32_32x32x16_bf16 v[64:79], v[132:135], v[88:91], v[64:79]
	v_add_u32_e32 v102, s8, v102
	v_mfma_f32_32x32x16_bf16 v[64:79], v[136:139], v[84:87], v[64:79]
	v_add_u32_e32 v104, s8, v104
	v_mfma_f32_32x32x16_bf16 v[64:79], v[140:143], v[80:83], v[64:79]
	s_cbranch_scc1 .Lhw_d1_b_dtd1bias2

; #define SBAR() __builtin_amdgcn_sched_barrier(0)
; #define ATT_DMA_K(t) do { const bf16_t* kg_ = Kh + (size_t)(t) * 64 * LDK; LAS unsigned char* sb_ = lds + ((t) & 3) * KBUF; \
;     _Pragma("unroll") for (int i_ = 0; i_ < NKP; ++i_) __builtin_amdgcn_global_load_lds((const unsigned*)(kg_ + kgo[i_]), (LAS unsigned*)(sb_ + (wid + 8 * i_) * 1024), 16, 0, 0); } while (0)
; #define ATT_DMA_V(t, vs) do { const bf16_t* vg_ = Vh + (size_t)(t) * 64 * LDV; LAS unsigned char* sb_ = lds + V_OFF + (vs) * SHM_V; \
;     _Pragma("unroll") for (int i_ = 0; i_ < 2; ++i_) __builtin_amdgcn_global_load_lds((const unsigned*)(vg_ + vgo[i_]), (LAS unsigned*)(sb_ + (2 * wid + i_) * 1024), 16, 0, 0); } while (0)
; #define ATT_SEG(t) do { if constexpr (MODE != 0) { if (((t) == tL && tL > 0) || (t) == tR) { const float f_ = (t) == tR ? fR : fL; l_reg *= f_; \
;     _Pragma("unroll") for (int d = 0; d < 4; ++d) _Pragma("unroll") for (int r = 0; r < 16; ++r) o[d][r] *= f_; } } } while (0)
; #define ATT_TOP(N) do { asm volatile("s_waitcnt vmcnt(%0)" :: "n"(N) : "memory"); __builtin_amdgcn_s_barrier(); asm volatile("" ::: "memory"); } while (0)
; DI void expsum(f32x16& p, float& l_reg, bf16x8& pa0, bf16x8& pa1) {
; #pragma unroll
;     for (int r = 0; r < 16; ++r) p[r] = __builtin_amdgcn_exp2f(p[r]);
;     float ps = 0.f;
; #pragma unroll
;     for (int r = 0; r < 16; ++r) ps += p[r];
;     l_reg += ps; asm volatile("" : "+v"(l_reg));
;     ...
;     ATT_PK4(p, 0, pa0); ATT_PK4(p, 8, pa1);
;     ...
; }
; template <int DQK, int MODE, int LDQ, int LDK, int LDV> ...
;     ...
;     f32x16 pA, pB; bf16x8 pa0, pa1;
;     int v0 = 0, v1 = 1, v2 = 2;
;     ATT_TOP(NKP + 2);
;     { bf16x8 kf[NDA]; k_reads<DQK, 0, NDA>(kf, lds, 0, r32, hi); ATT_LGKM0(); qk_mma<0, NDA>(pA, kf, qr);
;       if constexpr (ND0 > NDA) { bf16x8 kg[ND0 - NDA]; k_reads<DQK, NDA, ND0>(kg, lds, 0, r32, hi); ATT_LGKM0(); qk_mma<NDA, ND0>(pA, kg, qr); }
;       ATT_BIAS(pA, 0, 0); }
;     if (wid >= 4) __builtin_amdgcn_s_setprio(1);
;     for (int j = 0; j < NT; ++j) {
;         if (j + 2 < NT) ATT_TOP(NKP + 2); else ATT_TOP(0);
;         if (j + 3 < NT) ATT_DMA_K(j + 3);
;         if (j + 2 < NT) ATT_DMA_V(j + 2, v2);
;         ATT_SEG(j); SBAR();
;         ATT_STEP(pA, pB, 0, v0, true, 1, j);
;         ATT_STEP(pB, pA, 1, v0, (j + 1 < NT), 0, j + 1);
;         { const int t_ = v0; v0 = v1; v1 = v2; v2 = t_; }
;     }
.LBB0_1955:
	ds_read_b128 v[124:127], v196
	ds_read_b128 v[132:135], v197
	ds_read_b128 v[136:139], v198
	ds_read_b128 v[140:143], v199
	ds_read_b64_tr_b16 v[144:145], v121 offset:0x2000
	ds_read_b64_tr_b16 v[146:147], v121 offset:0x2800
	ds_read_b64_tr_b16 v[148:149], v121 offset:0x3000
	ds_read_b64_tr_b16 v[150:151], v121 offset:0x3800
	ds_read_b64_tr_b16 v[152:153], v121 offset:0x2200
	ds_read_b64_tr_b16 v[154:155], v121 offset:0x2a00
	ds_read_b64_tr_b16 v[156:157], v121 offset:0x3200
	ds_read_b64_tr_b16 v[158:159], v121 offset:0x3a00
	ds_read_b64_tr_b16 v[162:163], v121 offset:0x2400
	ds_read_b64_tr_b16 v[164:165], v121 offset:0x2c00
	ds_read_b64_tr_b16 v[166:167], v121 offset:0x3400
	ds_read_b64_tr_b16 v[168:169], v121 offset:0x3c00
	ds_read_b64_tr_b16 v[170:171], v121 offset:0x2600
	ds_read_b64_tr_b16 v[172:173], v121 offset:0x2e00
	ds_read_b64_tr_b16 v[174:175], v121 offset:0x3600
	ds_read_b64_tr_b16 v[176:177], v121 offset:0x3e00
	s_setprio 1
	v_exp_f32_e32 v64, v64
	v_exp_f32_e32 v65, v65
	v_exp_f32_e32 v66, v66
	v_exp_f32_e32 v67, v67
	v_exp_f32_e32 v68, v68
	v_exp_f32_e32 v69, v69
	v_add_f32_e32 v121, v65, v64
	v_exp_f32_e32 v70, v70
	v_add_f32_e32 v121, v66, v121
	v_exp_f32_e32 v71, v71
	v_add_f32_e32 v121, v67, v121
	v_exp_f32_e32 v72, v72
	v_add_f32_e32 v121, v68, v121
	v_exp_f32_e32 v73, v73
	v_add_f32_e32 v121, v69, v121
	v_exp_f32_e32 v74, v74
	v_add_f32_e32 v121, v70, v121
	v_exp_f32_e32 v75, v75
	v_add_f32_e32 v121, v71, v121
	v_exp_f32_e32 v76, v76
	v_add_f32_e32 v121, v72, v121
	v_exp_f32_e32 v77, v77
	v_add_f32_e32 v121, v73, v121
	v_exp_f32_e32 v78, v78
	v_add_f32_e32 v121, v74, v121
	v_exp_f32_e32 v79, v79
	v_add_f32_e32 v121, v75, v121
	v_add_f32_e32 v121, v76, v121
	v_add_f32_e32 v121, v77, v121
	v_add_f32_e32 v121, v78, v121
	v_add_f32_e32 v121, v79, v121
	v_add_f32_e32 v120, v120, v121
	v_cvt_pk_bf16_f32 v64, v64, v65
	v_cvt_pk_bf16_f32 v65, v66, v67
	v_cvt_pk_bf16_f32 v66, v68, v69
	v_cvt_pk_bf16_f32 v67, v70, v71
	v_cvt_pk_bf16_f32 v68, v72, v73
	v_cvt_pk_bf16_f32 v69, v74, v75
	v_cvt_pk_bf16_f32 v70, v76, v77
	v_cvt_pk_bf16_f32 v71, v78, v79
	s_waitcnt lgkmcnt(0)
	s_setprio 2
	v_mfma_f32_32x32x16_bf16 v[0:15], v[64:67], v[144:147], v[0:15]
	s_sub_i32 s74, s0, s47
	s_cmp_lt_u32 s74, s100
	v_mfma_f32_32x32x16_bf16 v[48:63], v[64:67], v[152:155], v[48:63]
	v_mfma_f32_32x32x16_bf16 v[16:31], v[64:67], v[162:165], v[16:31]
	v_mfma_f32_32x32x16_bf16 v[32:47], v[64:67], v[170:173], v[32:47]
	v_mfma_f32_32x32x16_bf16 v[0:15], v[68:71], v[148:151], v[0:15]
	v_mfma_f32_32x32x16_bf16 v[48:63], v[68:71], v[156:159], v[48:63]
	v_mfma_f32_32x32x16_bf16 v[16:31], v[68:71], v[166:169], v[16:31]
	v_mfma_f32_32x32x16_bf16 v[32:47], v[68:71], v[174:177], v[32:47]
	v_lshl_add_u32 v121, s49, 14, v106
	v_mfma_f32_32x32x16_bf16 v[64:79], v[124:127], v[92:95], 0
	v_add_u32_e32 v100, s8, v100
	v_mfma_f32_32x32x16_bf16 v[64:79], v[132:135], v[88:91], v[64:79]
	v_add_u32_e32 v102, s8, v102
	v_mfma_f32_32x32x16_bf16 v[64:79], v[136:139], v[84:87], v[64:79]
	v_add_u32_e32 v104, s8, v104
	v_mfma_f32_32x32x16_bf16 v[64:79], v[140:143], v[80:83], v[64:79]
	s_cbranch_scc1 .Ldt_d1_bias2
